# v51: v50 + passB K/V tile requests issued right after the Q-tile requests (before Q staging, stabiliser scan and two barriers), copied to consumer registers later
# speedup vs baseline: 1.0054x; 1.0054x over previous
; #define LAS __attribute__((address_space(3)))
; __device__ void passB_unit(const Params& p, LAS unsigned char* lds, int u, bool do_store = true) {
;     ...
;     { const int d = tid >> 8, k = tid & 255; nvec[tid] = ((const float*)(p.ws + OFF_NST))[(size_t)((sid0 + d) * 16 + c) * 256 + k]; }
; #pragma unroll
;     for (int i = 0; i < 8; ++i) { const int id = tid + 512 * i; const int w = id >> 9, m = (id >> 7) & 3, bj = (id >> 6) & 1, ln = id & 63;
;         *(LAS u32x4*)(Qs + ((w >> 2) * 64 + m * 16 + (ln & 15)) * 264 + bj * 128 + (w & 3) * 32 + (ln >> 4) * 8) = __builtin_nontemporal_load((const u32x4*)(Qg + (size_t)((w * 16 + m * 2 + bj) * 64 + ln) * 8)); }
;     ...
;     const bf16_t* Kg = (const bf16_t*)(p.ws + OFF_K) + (size_t)((b * 16 + c) * 4 + h) * 32768 + (size_t)(w4 * 2 * 8) * 512 + (fr * 4 + fq) * 8;
;     bf16x8 kfa[8][2];
; #pragma unroll
;     for (int ks = 0; ks < 8; ++ks)
; #pragma unroll
;         for (int nt = 0; nt < 2; ++nt) kfa[ks][nt] = *(const bf16x8*)(Kg + (size_t)(nt * 8 + ks) * 512);
.LBB0_537:
	s_or_b64 exec, exec, s[4:5]
	s_lshl_b32 s53, s40, 11
	s_or_b32 s4, s10, s53
	s_ashr_i32 s4, s4, 6
	s_or_b32 s4, s4, s34
	s_ashr_i32 s5, s4, 31
	s_lshl_b64 s[4:5], s[4:5], 17
	v_readlane_b32 s6, v254, 35
	v_readlane_b32 s7, v254, 36
	s_add_u32 s44, s6, s4
	s_addc_u32 s45, s7, s5
	s_lshl_b32 s4, s40, 3
	s_lshl_b32 s5, s34, 1
	s_or_b32 s50, s5, s4
	v_ashrrev_i32_e32 v62, 8, v196
	v_add_u32_e32 v1, s50, v62
	v_add_u32_e32 v38, 0x200, v196
	v_lshl_or_b32 v2, v1, 4, s52
	v_bfe_u32 v34, v196, 7, 2
	v_ashrrev_i32_e32 v39, 9, v38
	v_ashrrev_i32_e32 v3, 31, v2
	v_bfe_u32 v198, v196, 6, 1
	v_lshlrev_b32_e32 v199, 1, v34
	v_lshlrev_b32_e32 v6, 4, v39
	v_lshlrev_b64 v[2:3], 10, v[2:3]
	v_mov_b32_e32 v1, 2
	v_or3_b32 v6, v199, v6, v198
	v_lshl_add_u64 v[2:3], s[16:17], 0, v[2:3]
	v_lshlrev_b32_sdwa v60, v1, v196 dst_sel:DWORD dst_unused:UNUSED_PAD src0_sel:DWORD src1_sel:BYTE_0
	v_mov_b32_e32 v61, 0
	v_lshl_or_b32 v6, v6, 6, v197
	v_lshl_add_u64 v[2:3], v[2:3], 0, v[60:61]
	v_ashrrev_i32_e32 v7, 31, v6
	global_load_dword v1, v[2:3], off
	v_ashrrev_i32_e32 v35, 9, v196
	v_lshl_add_u64 v[6:7], v[6:7], 4, s[44:45]
	global_load_dwordx4 v[6:9], v[6:7], off nt
	v_lshlrev_b32_e32 v2, 4, v35
	v_or3_b32 v2, v199, v2, v198
	v_lshl_or_b32 v2, v2, 6, v197
	v_ashrrev_i32_e32 v3, 31, v2
	v_lshl_add_u64 v[2:3], v[2:3], 4, s[44:45]
	global_load_dwordx4 v[2:5], v[2:3], off nt
	v_add_u32_e32 v40, 0x400, v196
	v_ashrrev_i32_e32 v41, 9, v40
	v_lshlrev_b32_e32 v10, 4, v41
	v_or3_b32 v10, v199, v10, v198
	v_lshl_or_b32 v10, v10, 6, v197
	v_ashrrev_i32_e32 v11, 31, v10
	v_lshl_add_u64 v[10:11], v[10:11], 4, s[44:45]
	v_add_u32_e32 v42, 0x600, v196
	global_load_dwordx4 v[10:13], v[10:11], off nt
	v_ashrrev_i32_e32 v43, 9, v42
	v_lshlrev_b32_e32 v14, 4, v43
	v_or3_b32 v14, v199, v14, v198
	v_lshl_or_b32 v14, v14, 6, v197
	v_ashrrev_i32_e32 v15, 31, v14
	v_lshl_add_u64 v[14:15], v[14:15], 4, s[44:45]
	v_add_u32_e32 v44, 0x800, v196
	global_load_dwordx4 v[14:17], v[14:15], off nt
	v_ashrrev_i32_e32 v45, 9, v44
	v_lshlrev_b32_e32 v18, 4, v45
	v_or3_b32 v18, v199, v18, v198
	v_lshl_or_b32 v18, v18, 6, v197
	v_ashrrev_i32_e32 v19, 31, v18
	v_lshl_add_u64 v[18:19], v[18:19], 4, s[44:45]
	v_add_u32_e32 v46, 0xa00, v196
	global_load_dwordx4 v[18:21], v[18:19], off nt
	v_ashrrev_i32_e32 v47, 9, v46
	v_lshlrev_b32_e32 v22, 4, v47
	v_or3_b32 v22, v199, v22, v198
	v_lshl_or_b32 v22, v22, 6, v197
	v_ashrrev_i32_e32 v23, 31, v22
	v_lshl_add_u64 v[22:23], v[22:23], 4, s[44:45]
	v_add_u32_e32 v48, 0xc00, v196
	global_load_dwordx4 v[22:25], v[22:23], off nt
	v_ashrrev_i32_e32 v49, 9, v48
	v_lshlrev_b32_e32 v26, 4, v49
	v_or3_b32 v26, v199, v26, v198
	v_lshl_or_b32 v26, v26, 6, v197
	v_ashrrev_i32_e32 v27, 31, v26
	v_lshl_add_u64 v[26:27], v[26:27], 4, s[44:45]
	v_add_u32_e32 v50, 0xe00, v196
	global_load_dwordx4 v[26:29], v[26:27], off nt
	v_ashrrev_i32_e32 v51, 9, v50
	v_lshlrev_b32_e32 v30, 4, v51
	v_or3_b32 v30, v199, v30, v198
	v_lshl_or_b32 v30, v30, 6, v197
	v_ashrrev_i32_e32 v31, 31, v30
	v_lshl_add_u64 v[30:31], v[30:31], 4, s[44:45]
	global_load_dwordx4 v[30:33], v[30:31], off nt
	s_lshl_b32 s62, s40, 4
	s_or_b32 s62, s62, s52
	s_lshl_b32 s62, s62, 2
	s_or_b32 s62, s62, s34
	s_ashr_i32 s63, s62, 31
	s_lshl_b64 s[62:63], s[62:63], 16
	s_add_u32 s62, s30, s62
	s_addc_u32 s63, s31, s63
	s_add_u32 s62, s62, 0x1000
	s_addc_u32 s63, s63, 0
	v_and_b32_e32 v160, 15, v196
	v_lshrrev_b32_e32 v161, 4, v197
	v_lshlrev_b32_e32 v160, 5, v160
	v_lshl_or_b32 v160, v161, 3, v160
	v_lshlrev_b32_e32 v160, 1, v160
	v_bfe_u32 v161, v196, 6, 2
	v_lshl_add_u32 v160, v161, 14, v160
	v_mov_b32_e32 v161, 0
	v_lshl_add_u64 v[162:163], s[62:63], 0, v[160:161]
	s_add_u32 s62, s62, 0x2000
	s_addc_u32 s63, s63, 0
	v_lshl_add_u64 v[164:165], s[62:63], 0, v[160:161]
	global_load_dwordx4 v[94:97], v[162:163], off offset:-4096
	global_load_dwordx4 v[98:101], v[162:163], off offset:-3072
	global_load_dwordx4 v[102:105], v[164:165], off offset:-4096
	global_load_dwordx4 v[106:109], v[164:165], off offset:-3072
	global_load_dwordx4 v[110:113], v[162:163], off offset:-2048
	global_load_dwordx4 v[114:117], v[162:163], off offset:-1024
	global_load_dwordx4 v[118:121], v[164:165], off offset:-2048
	global_load_dwordx4 v[122:125], v[164:165], off offset:-1024
	global_load_dwordx4 v[126:129], v[162:163], off
	global_load_dwordx4 v[130:133], v[162:163], off offset:1024
	global_load_dwordx4 v[134:137], v[164:165], off
	global_load_dwordx4 v[138:141], v[164:165], off offset:1024
	global_load_dwordx4 v[142:145], v[162:163], off offset:2048
	global_load_dwordx4 v[146:149], v[162:163], off offset:3072
	global_load_dwordx4 v[150:153], v[164:165], off offset:2048
	global_load_dwordx4 v[154:157], v[164:165], off offset:3072
	v_lshl_add_u32 v92, v196, 2, 0
	v_lshrrev_b32_e32 v36, 1, v196
	v_add_u32_e32 v37, 0x23400, v92
	v_and_b32_e32 v201, 15, v196
	v_lshlrev_b32_e32 v202, 4, v34
	v_lshlrev_b32_e32 v203, 8, v198
	v_add_u32_e32 v34, 0, v203
	s_movk_i32 s6, 0x210
	v_and_b32_e32 v60, 64, v196
	v_mov_b32_e32 v70, v61
	s_waitcnt vmcnt(24)
; #define LAS __attribute__((address_space(3)))
; __device__ void passB_unit(const Params& p, LAS unsigned char* lds, int u, bool do_store = true) {
;     ...
;     for (int i = 0; i < 8; ++i) { const int id = tid + 512 * i; const int w = id >> 9, m = (id >> 7) & 3, bj = (id >> 6) & 1, ln = id & 63;
;         *(LAS u32x4*)(Qs + ((w >> 2) * 64 + m * 16 + (ln & 15)) * 264 + bj * 128 + (w & 3) * 32 + (ln >> 4) * 8) = __builtin_nontemporal_load((const u32x4*)(Qg + (size_t)((w * 16 + m * 2 + bj) * 64 + ln) * 8)); }
;     __syncthreads();
	ds_write_b32 v37, v1
	v_and_b32_e32 v1, 24, v36
	v_ashrrev_i32_e32 v36, 5, v196
	v_and_b32_e32 v36, 0xfffffc0, v36
	v_or3_b32 v36, v36, v202, v201
	v_mad_u64_u32 v[36:37], s[4:5], v36, s6, v[34:35]
	v_lshlrev_b32_e32 v35, 6, v35
	v_and_b32_e32 v35, 0xc0, v35
	v_lshlrev_b32_e32 v200, 1, v1
	v_add3_u32 v1, v36, v35, v200
	s_waitcnt vmcnt(22)
	ds_write_b128 v1, v[2:5]
	v_ashrrev_i32_e32 v1, 5, v38
	v_and_b32_e32 v1, 0xfffffc0, v1
	v_or3_b32 v1, v202, v1, v201
	v_mad_u64_u32 v[2:3], s[4:5], v1, s6, v[34:35]
	v_lshlrev_b32_e32 v1, 6, v39
	v_and_b32_e32 v1, 0xc0, v1
	v_add3_u32 v1, v2, v1, v200
	ds_write_b128 v1, v[6:9]
	v_ashrrev_i32_e32 v1, 5, v40
	v_and_b32_e32 v1, 0xfffffc0, v1
	v_or3_b32 v1, v202, v1, v201
	v_mad_u64_u32 v[2:3], s[4:5], v1, s6, v[34:35]
	v_lshlrev_b32_e32 v1, 6, v41
	v_and_b32_e32 v1, 0xc0, v1
	v_add3_u32 v1, v2, v1, v200
	s_waitcnt vmcnt(21)
	ds_write_b128 v1, v[10:13]
	v_ashrrev_i32_e32 v1, 5, v42
	v_and_b32_e32 v1, 0xfffffc0, v1
	v_or3_b32 v1, v202, v1, v201
	v_mad_u64_u32 v[2:3], s[4:5], v1, s6, v[34:35]
	v_lshlrev_b32_e32 v1, 6, v43
	v_and_b32_e32 v1, 0xc0, v1
	v_add3_u32 v1, v2, v1, v200
	s_waitcnt vmcnt(20)
	ds_write_b128 v1, v[14:17]
	v_ashrrev_i32_e32 v1, 5, v44
	v_and_b32_e32 v1, 0xfffffc0, v1
	v_or3_b32 v1, v202, v1, v201
	v_mad_u64_u32 v[2:3], s[4:5], v1, s6, v[34:35]
	v_lshlrev_b32_e32 v1, 6, v45
	v_and_b32_e32 v1, 0xc0, v1
	v_add3_u32 v1, v2, v1, v200
	s_waitcnt vmcnt(19)
	ds_write_b128 v1, v[18:21]
	v_ashrrev_i32_e32 v1, 5, v46
	v_and_b32_e32 v1, 0xfffffc0, v1
	v_or3_b32 v1, v202, v1, v201
	v_mad_u64_u32 v[2:3], s[4:5], v1, s6, v[34:35]
	v_lshlrev_b32_e32 v1, 6, v47
	v_and_b32_e32 v1, 0xc0, v1
	v_add3_u32 v1, v2, v1, v200
	s_waitcnt vmcnt(18)
	ds_write_b128 v1, v[22:25]
	v_ashrrev_i32_e32 v1, 5, v48
	v_and_b32_e32 v1, 0xfffffc0, v1
	v_or3_b32 v1, v202, v1, v201
	v_mad_u64_u32 v[2:3], s[4:5], v1, s6, v[34:35]
	v_lshlrev_b32_e32 v1, 6, v49
	v_and_b32_e32 v1, 0xc0, v1
	v_add3_u32 v1, v2, v1, v200
	s_waitcnt vmcnt(17)
	ds_write_b128 v1, v[26:29]
	v_ashrrev_i32_e32 v1, 5, v50
	v_and_b32_e32 v1, 0xfffffc0, v1
	v_or3_b32 v1, v202, v1, v201
	v_mad_u64_u32 v[2:3], s[4:5], v1, s6, v[34:35]
	v_lshlrev_b32_e32 v1, 6, v51
	v_and_b32_e32 v1, 0xc0, v1
	v_add3_u32 v1, v2, v1, v200
	s_waitcnt vmcnt(16)
	ds_write_b128 v1, v[30:33]
	s_waitcnt lgkmcnt(0)
	s_barrier
	s_and_saveexec_b64 s[6:7], s[0:1]
	s_cbranch_execz .LBB0_543
	v_cmp_ne_u32_e32 vcc, 0, v60
	s_and_saveexec_b64 s[4:5], vcc
	s_cbranch_execz .LBB0_540
	v_lshlrev_b32_e32 v1, 2, v68
	s_add_i32 s10, 0, 0x21800
	v_add3_u32 v1, s10, v1, -4
	ds_read_b32 v1, v1
	s_waitcnt lgkmcnt(0)
	v_add_f32_e32 v69, v69, v1

; __device__ void passB_unit(const Params& p, LAS unsigned char* lds, int u, bool do_store = true) {
;     ...
;     const bf16_t* Kg = (const bf16_t*)(p.ws + OFF_K) + (size_t)((b * 16 + c) * 4 + h) * 32768 + (size_t)(w4 * 2 * 8) * 512 + (fr * 4 + fq) * 8;
;     bf16x8 kfa[8][2];
; #pragma unroll
;     for (int ks = 0; ks < 8; ++ks)
; #pragma unroll
;         for (int nt = 0; nt < 2; ++nt) kfa[ks][nt] = *(const bf16x8*)(Kg + (size_t)(nt * 8 + ks) * 512);
;     if (tid < 256) { const int d = tid >> 7, t = sc_t; if (wid & 1) sc_pm = fmaxf(sc_pm, wmax[wid - 1]);
.LBB0_543:
	s_or_b64 exec, exec, s[6:7]
	s_lshl_b32 s56, s40, 4
	s_or_b32 s42, s56, s52
	s_lshl_b32 s4, s42, 2
	s_or_b32 s4, s4, s34
	s_ashr_i32 s5, s4, 31
	s_lshl_b64 s[4:5], s[4:5], 16
	v_lshrrev_b32_e32 v93, 4, v197
	v_bfe_u32 v223, v196, 6, 2
	s_add_u32 s4, s30, s4
	v_lshlrev_b32_e32 v2, 5, v201
	s_addc_u32 s5, s31, s5
	v_lshlrev_b32_e32 v88, 14, v223
	v_mov_b32_e32 v89, 0
	v_lshl_or_b32 v2, v93, 3, v2
	v_lshl_add_u64 v[0:1], s[4:5], 0, v[88:89]
	v_lshlrev_b32_e32 v90, 1, v2
	v_mov_b32_e32 v91, v89
	v_lshl_add_u64 v[0:1], v[0:1], 0, v[90:91]
	s_movk_i32 s4, 0x2000
	v_add_co_u32_e32 v2, vcc, s4, v0
	s_movk_i32 s4, 0x1000
	s_nop 0
	v_addc_co_u32_e32 v3, vcc, 0, v1, vcc
	s_waitcnt lgkmcnt(0)
	s_barrier
	s_waitcnt vmcnt(0)
	v_mov_b32_e32 v52, v94
	v_mov_b32_e32 v53, v95
	v_mov_b32_e32 v54, v96
	v_mov_b32_e32 v55, v97
	v_mov_b32_e32 v44, v98
	v_mov_b32_e32 v45, v99
	v_mov_b32_e32 v46, v100
	v_mov_b32_e32 v47, v101
	v_mov_b32_e32 v56, v102
	v_mov_b32_e32 v57, v103
	v_mov_b32_e32 v58, v104
	v_mov_b32_e32 v59, v105
	v_mov_b32_e32 v48, v106
	v_mov_b32_e32 v49, v107
	v_mov_b32_e32 v50, v108
	v_mov_b32_e32 v51, v109
	v_mov_b32_e32 v36, v110
	v_mov_b32_e32 v37, v111
	v_mov_b32_e32 v38, v112
	v_mov_b32_e32 v39, v113
	v_mov_b32_e32 v28, v114
	v_mov_b32_e32 v29, v115
	v_mov_b32_e32 v30, v116
	v_mov_b32_e32 v31, v117
	v_mov_b32_e32 v40, v118
	v_mov_b32_e32 v41, v119
	v_mov_b32_e32 v42, v120
	v_mov_b32_e32 v43, v121
	v_mov_b32_e32 v32, v122
	v_mov_b32_e32 v33, v123
	v_mov_b32_e32 v34, v124
	v_mov_b32_e32 v35, v125
	v_mov_b32_e32 v20, v126
	v_mov_b32_e32 v21, v127
	v_mov_b32_e32 v22, v128
	v_mov_b32_e32 v23, v129
	v_mov_b32_e32 v12, v130
	v_mov_b32_e32 v13, v131
	v_mov_b32_e32 v14, v132
	v_mov_b32_e32 v15, v133
	v_mov_b32_e32 v24, v134
	v_mov_b32_e32 v25, v135
	v_mov_b32_e32 v26, v136
	v_mov_b32_e32 v27, v137
	v_mov_b32_e32 v16, v138
	v_mov_b32_e32 v17, v139
	v_mov_b32_e32 v18, v140
	v_mov_b32_e32 v19, v141
	v_mov_b32_e32 v8, v142
	v_mov_b32_e32 v9, v143
	v_mov_b32_e32 v10, v144
	v_mov_b32_e32 v11, v145
	v_mov_b32_e32 v0, v146
	v_mov_b32_e32 v1, v147
	v_mov_b32_e32 v2, v148
	v_mov_b32_e32 v3, v149
	v_mov_b32_e32 v4, v150
	v_mov_b32_e32 v5, v151
	v_mov_b32_e32 v6, v152
	v_mov_b32_e32 v7, v153
	v_mov_b32_e32 v64, v154
	v_mov_b32_e32 v65, v155
	v_mov_b32_e32 v66, v156
	v_mov_b32_e32 v67, v157
	s_and_saveexec_b64 s[4:5], s[0:1]
	s_cbranch_execz .LBB0_549
	v_cmp_ne_u32_e32 vcc, 0, v60
	s_and_saveexec_b64 s[6:7], vcc
	s_cbranch_execz .LBB0_546
	v_lshlrev_b32_e32 v60, 2, v68
	s_add_i32 s10, 0, 0x21820
	v_add3_u32 v60, s10, v60, -4
	ds_read_b32 v60, v60
	v_max_f32_e32 v68, v70, v70
	s_waitcnt lgkmcnt(0)
	v_max_f32_e32 v60, v60, v60
	v_max_f32_e32 v70, v68, v60

; #define LAS __attribute__((address_space(3)))
; __device__ void passB_unit(const Params& p, LAS unsigned char* lds, int u, bool do_store = true) {
;     ...
;     { const int d = tid >> 8, k = tid & 255; nvec[tid] = ((const float*)(p.ws + OFF_NST))[(size_t)((sid0 + d) * 16 + c) * 256 + k]; }
; #pragma unroll
;     for (int i = 0; i < 8; ++i) { const int id = tid + 512 * i; const int w = id >> 9, m = (id >> 7) & 3, bj = (id >> 6) & 1, ln = id & 63;
;         *(LAS u32x4*)(Qs + ((w >> 2) * 64 + m * 16 + (ln & 15)) * 264 + bj * 128 + (w & 3) * 32 + (ln >> 4) * 8) = __builtin_nontemporal_load((const u32x4*)(Qg + (size_t)((w * 16 + m * 2 + bj) * 64 + ln) * 8)); }
;     ...
;     const bf16_t* Kg = (const bf16_t*)(p.ws + OFF_K) + (size_t)((b * 16 + c) * 4 + h) * 32768 + (size_t)(w4 * 2 * 8) * 512 + (fr * 4 + fq) * 8;
;     bf16x8 kfa[8][2];
; #pragma unroll
;     for (int ks = 0; ks < 8; ++ks)
; #pragma unroll
;         for (int nt = 0; nt < 2; ++nt) kfa[ks][nt] = *(const bf16x8*)(Kg + (size_t)(nt * 8 + ks) * 512);
.LBB0_573:
	s_or_b64 exec, exec, s[4:5]
	s_or_b32 s4, s10, s53
	s_ashr_i32 s4, s4, 6
	s_and_b32 s4, s4, -4
	s_or_b32 s4, s4, s34
	v_ashrrev_i32_e32 v62, 8, v196
	v_add_u32_e32 v7, s50, v62
	s_ashr_i32 s5, s4, 31
	v_add_u32_e32 v44, 0x200, v196
	v_lshl_or_b32 v8, v7, 4, s24
	s_lshl_b64 s[4:5], s[4:5], 17
	v_readlane_b32 s6, v254, 35
	v_bfe_u32 v40, v196, 7, 2
	v_ashrrev_i32_e32 v45, 9, v44
	v_ashrrev_i32_e32 v9, 31, v8
	v_readlane_b32 s7, v254, 36
	s_add_u32 s4, s6, s4
	v_bfe_u32 v198, v196, 6, 1
	v_lshlrev_b32_e32 v199, 1, v40
	v_lshlrev_b32_e32 v12, 4, v45
	v_lshlrev_b64 v[8:9], 10, v[8:9]
	v_mov_b32_e32 v7, 2
	s_addc_u32 s5, s7, s5
	v_or3_b32 v12, v199, v12, v198
	v_lshl_add_u64 v[8:9], s[16:17], 0, v[8:9]
	v_lshlrev_b32_sdwa v60, v7, v196 dst_sel:DWORD dst_unused:UNUSED_PAD src0_sel:DWORD src1_sel:BYTE_0
	v_mov_b32_e32 v61, 0
	s_add_u32 s16, s4, 0x2000
	v_lshl_or_b32 v12, v12, 6, v197
	v_lshl_add_u64 v[8:9], v[8:9], 0, v[60:61]
	s_addc_u32 s17, s5, 0
	v_ashrrev_i32_e32 v13, 31, v12
	global_load_dword v7, v[8:9], off
	v_ashrrev_i32_e32 v41, 9, v196
	v_lshl_add_u64 v[12:13], v[12:13], 4, s[16:17]
	global_load_dwordx4 v[12:15], v[12:13], off nt
	v_lshlrev_b32_e32 v8, 4, v41
	v_or3_b32 v8, v199, v8, v198
	v_lshl_or_b32 v8, v8, 6, v197
	v_ashrrev_i32_e32 v9, 31, v8
	v_lshl_add_u64 v[8:9], v[8:9], 4, s[16:17]
	global_load_dwordx4 v[8:11], v[8:9], off nt
	v_add_u32_e32 v46, 0x400, v196
	v_ashrrev_i32_e32 v47, 9, v46
	v_lshlrev_b32_e32 v16, 4, v47
	v_or3_b32 v16, v199, v16, v198
	v_lshl_or_b32 v16, v16, 6, v197
	v_ashrrev_i32_e32 v17, 31, v16
	v_lshl_add_u64 v[16:17], v[16:17], 4, s[16:17]
	v_add_u32_e32 v48, 0x600, v196
	global_load_dwordx4 v[16:19], v[16:17], off nt
	v_ashrrev_i32_e32 v49, 9, v48
	v_lshlrev_b32_e32 v20, 4, v49
	v_or3_b32 v20, v199, v20, v198
	v_lshl_or_b32 v20, v20, 6, v197
	v_ashrrev_i32_e32 v21, 31, v20
	v_lshl_add_u64 v[20:21], v[20:21], 4, s[16:17]
	v_add_u32_e32 v50, 0x800, v196
	global_load_dwordx4 v[20:23], v[20:21], off nt
	v_ashrrev_i32_e32 v51, 9, v50
	v_lshlrev_b32_e32 v24, 4, v51
	v_or3_b32 v24, v199, v24, v198
	v_lshl_or_b32 v24, v24, 6, v197
	v_ashrrev_i32_e32 v25, 31, v24
	v_lshl_add_u64 v[24:25], v[24:25], 4, s[16:17]
	v_add_u32_e32 v52, 0xa00, v196
	global_load_dwordx4 v[24:27], v[24:25], off nt
	v_ashrrev_i32_e32 v53, 9, v52
	v_lshlrev_b32_e32 v28, 4, v53
	v_or3_b32 v28, v199, v28, v198
	v_lshl_or_b32 v28, v28, 6, v197
	v_ashrrev_i32_e32 v29, 31, v28
	v_lshl_add_u64 v[28:29], v[28:29], 4, s[16:17]
	v_add_u32_e32 v54, 0xc00, v196
	global_load_dwordx4 v[28:31], v[28:29], off nt
	v_ashrrev_i32_e32 v55, 9, v54
	v_lshlrev_b32_e32 v32, 4, v55
	v_or3_b32 v32, v199, v32, v198
	v_lshl_or_b32 v32, v32, 6, v197
	v_ashrrev_i32_e32 v33, 31, v32
	v_lshl_add_u64 v[32:33], v[32:33], 4, s[16:17]
	v_add_u32_e32 v56, 0xe00, v196
	global_load_dwordx4 v[32:35], v[32:33], off nt
	v_ashrrev_i32_e32 v57, 9, v56
	v_lshlrev_b32_e32 v36, 4, v57
	v_or3_b32 v36, v199, v36, v198
	v_lshl_or_b32 v36, v36, 6, v197
	v_ashrrev_i32_e32 v37, 31, v36
	v_lshl_add_u64 v[36:37], v[36:37], 4, s[16:17]
	global_load_dwordx4 v[36:39], v[36:37], off nt
	s_or_b32 s62, s24, s56
	s_lshl_b32 s62, s62, 2
	s_or_b32 s62, s62, s34
	s_ashr_i32 s63, s62, 31
	s_lshl_b64 s[62:63], s[62:63], 16
	s_add_u32 s62, s30, s62
	s_addc_u32 s63, s31, s63
	s_add_u32 s62, s62, 0x1000
	s_addc_u32 s63, s63, 0
	v_and_b32_e32 v160, 15, v196
	v_lshrrev_b32_e32 v161, 4, v197
	v_lshlrev_b32_e32 v160, 5, v160
	v_lshl_or_b32 v160, v161, 3, v160
	v_lshlrev_b32_e32 v160, 1, v160
	v_bfe_u32 v161, v196, 6, 2
	v_lshl_add_u32 v160, v161, 14, v160
	v_mov_b32_e32 v161, 0
	v_lshl_add_u64 v[162:163], s[62:63], 0, v[160:161]
	s_add_u32 s62, s62, 0x2000
	s_addc_u32 s63, s63, 0
	v_lshl_add_u64 v[164:165], s[62:63], 0, v[160:161]
	global_load_dwordx4 v[94:97], v[162:163], off offset:-4096
	global_load_dwordx4 v[98:101], v[162:163], off offset:-3072
	global_load_dwordx4 v[102:105], v[164:165], off offset:-4096
	global_load_dwordx4 v[106:109], v[164:165], off offset:-3072
	global_load_dwordx4 v[110:113], v[162:163], off offset:-2048
	global_load_dwordx4 v[114:117], v[162:163], off offset:-1024
	global_load_dwordx4 v[118:121], v[164:165], off offset:-2048
	global_load_dwordx4 v[122:125], v[164:165], off offset:-1024
	global_load_dwordx4 v[126:129], v[162:163], off
	global_load_dwordx4 v[130:133], v[162:163], off offset:1024
	global_load_dwordx4 v[134:137], v[164:165], off
	global_load_dwordx4 v[138:141], v[164:165], off offset:1024
	global_load_dwordx4 v[142:145], v[162:163], off offset:2048
	global_load_dwordx4 v[146:149], v[162:163], off offset:3072
	global_load_dwordx4 v[150:153], v[164:165], off offset:2048
	global_load_dwordx4 v[154:157], v[164:165], off offset:3072
	v_lshl_add_u32 v92, v196, 2, 0
	v_add_u32_e32 v42, 0x23400, v92
	v_and_b32_e32 v201, 15, v196
	v_lshlrev_b32_e32 v202, 4, v40
	v_lshlrev_b32_e32 v203, 8, v198
	v_add_u32_e32 v40, 0, v203
	s_movk_i32 s6, 0x210
	v_and_b32_e32 v60, 64, v196
	v_mov_b32_e32 v70, v61
	s_waitcnt vmcnt(24)
; #define LAS __attribute__((address_space(3)))
; __device__ void passB_unit(const Params& p, LAS unsigned char* lds, int u, bool do_store = true) {
;     ...
;     for (int i = 0; i < 8; ++i) { const int id = tid + 512 * i; const int w = id >> 9, m = (id >> 7) & 3, bj = (id >> 6) & 1, ln = id & 63;
;         *(LAS u32x4*)(Qs + ((w >> 2) * 64 + m * 16 + (ln & 15)) * 264 + bj * 128 + (w & 3) * 32 + (ln >> 4) * 8) = __builtin_nontemporal_load((const u32x4*)(Qg + (size_t)((w * 16 + m * 2 + bj) * 64 + ln) * 8)); }
;     __syncthreads();
	ds_write_b32 v42, v7
	v_ashrrev_i32_e32 v42, 5, v196
	v_and_b32_e32 v42, 0xfffffc0, v42
	v_lshrrev_b32_e32 v7, 1, v196
	v_or3_b32 v42, v42, v202, v201
	v_and_b32_e32 v7, 24, v7
	v_mad_u64_u32 v[42:43], s[4:5], v42, s6, v[40:41]
	v_lshlrev_b32_e32 v41, 6, v41
	v_and_b32_e32 v41, 0xc0, v41
	v_lshlrev_b32_e32 v200, 1, v7
	v_add3_u32 v7, v42, v41, v200
	s_waitcnt vmcnt(22)
	ds_write_b128 v7, v[8:11]
	v_ashrrev_i32_e32 v7, 5, v44
	v_and_b32_e32 v7, 0xfffffc0, v7
	v_or3_b32 v7, v202, v7, v201
	v_mad_u64_u32 v[8:9], s[4:5], v7, s6, v[40:41]
	v_lshlrev_b32_e32 v7, 6, v45
	v_and_b32_e32 v7, 0xc0, v7
	v_add3_u32 v7, v8, v7, v200
	ds_write_b128 v7, v[12:15]
	v_ashrrev_i32_e32 v7, 5, v46
	v_and_b32_e32 v7, 0xfffffc0, v7
	v_or3_b32 v7, v202, v7, v201
	v_mad_u64_u32 v[8:9], s[4:5], v7, s6, v[40:41]
	v_lshlrev_b32_e32 v7, 6, v47
	v_and_b32_e32 v7, 0xc0, v7
	v_add3_u32 v7, v8, v7, v200
	s_waitcnt vmcnt(21)
	ds_write_b128 v7, v[16:19]
	v_ashrrev_i32_e32 v7, 5, v48
	v_and_b32_e32 v7, 0xfffffc0, v7
	v_or3_b32 v7, v202, v7, v201
	v_mad_u64_u32 v[8:9], s[4:5], v7, s6, v[40:41]
	v_lshlrev_b32_e32 v7, 6, v49
	v_and_b32_e32 v7, 0xc0, v7
	v_add3_u32 v7, v8, v7, v200
	s_waitcnt vmcnt(20)
	ds_write_b128 v7, v[20:23]
	v_ashrrev_i32_e32 v7, 5, v50
	v_and_b32_e32 v7, 0xfffffc0, v7
	v_or3_b32 v7, v202, v7, v201
	v_mad_u64_u32 v[8:9], s[4:5], v7, s6, v[40:41]
	v_lshlrev_b32_e32 v7, 6, v51
	v_and_b32_e32 v7, 0xc0, v7
	v_add3_u32 v7, v8, v7, v200
	s_waitcnt vmcnt(19)
	ds_write_b128 v7, v[24:27]
	v_ashrrev_i32_e32 v7, 5, v52
	v_and_b32_e32 v7, 0xfffffc0, v7
	v_or3_b32 v7, v202, v7, v201
	v_mad_u64_u32 v[8:9], s[4:5], v7, s6, v[40:41]
	v_lshlrev_b32_e32 v7, 6, v53
	v_and_b32_e32 v7, 0xc0, v7
	v_add3_u32 v7, v8, v7, v200
	s_waitcnt vmcnt(18)
	ds_write_b128 v7, v[28:31]
	v_ashrrev_i32_e32 v7, 5, v54
	v_and_b32_e32 v7, 0xfffffc0, v7
	v_or3_b32 v7, v202, v7, v201
	v_mad_u64_u32 v[8:9], s[4:5], v7, s6, v[40:41]
	v_lshlrev_b32_e32 v7, 6, v55
	v_and_b32_e32 v7, 0xc0, v7
	v_add3_u32 v7, v8, v7, v200
	s_waitcnt vmcnt(17)
	ds_write_b128 v7, v[32:35]
	v_ashrrev_i32_e32 v7, 5, v56
	v_and_b32_e32 v7, 0xfffffc0, v7
	v_or3_b32 v7, v202, v7, v201
	v_mad_u64_u32 v[8:9], s[4:5], v7, s6, v[40:41]
	v_lshlrev_b32_e32 v7, 6, v57
	v_and_b32_e32 v7, 0xc0, v7
	v_add3_u32 v7, v8, v7, v200
	s_waitcnt vmcnt(16)
	ds_write_b128 v7, v[36:39]
	s_waitcnt lgkmcnt(0)
	s_barrier
	s_and_saveexec_b64 s[6:7], s[0:1]
	s_cbranch_execz .LBB0_579
	v_cmp_ne_u32_e32 vcc, 0, v60
	s_and_saveexec_b64 s[4:5], vcc
	s_cbranch_execz .LBB0_576
	v_lshlrev_b32_e32 v7, 2, v68
	s_add_i32 s10, 0, 0x21800
	v_add3_u32 v7, s10, v7, -4
	ds_read_b32 v7, v7
	s_waitcnt lgkmcnt(0)
	v_add_f32_e32 v69, v69, v7

; __device__ void passB_unit(const Params& p, LAS unsigned char* lds, int u, bool do_store = true) {
;     ...
;     const bf16_t* Kg = (const bf16_t*)(p.ws + OFF_K) + (size_t)((b * 16 + c) * 4 + h) * 32768 + (size_t)(w4 * 2 * 8) * 512 + (fr * 4 + fq) * 8;
;     bf16x8 kfa[8][2];
; #pragma unroll
;     for (int ks = 0; ks < 8; ++ks)
; #pragma unroll
;         for (int nt = 0; nt < 2; ++nt) kfa[ks][nt] = *(const bf16x8*)(Kg + (size_t)(nt * 8 + ks) * 512);
;     if (tid < 256) { const int d = tid >> 7, t = sc_t; if (wid & 1) sc_pm = fmaxf(sc_pm, wmax[wid - 1]);
.LBB0_579:
	s_or_b64 exec, exec, s[6:7]
	s_or_b32 s40, s24, s56
	s_lshl_b32 s4, s40, 2
	s_or_b32 s4, s4, s34
	s_ashr_i32 s5, s4, 31
	s_lshl_b64 s[4:5], s[4:5], 16
	v_lshrrev_b32_e32 v93, 4, v197
	v_bfe_u32 v221, v196, 6, 2
	s_add_u32 s4, s30, s4
	v_lshlrev_b32_e32 v2, 5, v201
	s_addc_u32 s5, s31, s5
	v_lshlrev_b32_e32 v88, 14, v221
	v_mov_b32_e32 v89, 0
	v_lshl_or_b32 v2, v93, 3, v2
	v_lshl_add_u64 v[0:1], s[4:5], 0, v[88:89]
	v_lshlrev_b32_e32 v90, 1, v2
	v_mov_b32_e32 v91, v89
	v_lshl_add_u64 v[0:1], v[0:1], 0, v[90:91]
	s_movk_i32 s4, 0x2000
	v_add_co_u32_e32 v2, vcc, s4, v0
	s_movk_i32 s4, 0x1000
	s_nop 0
	v_addc_co_u32_e32 v3, vcc, 0, v1, vcc
	s_waitcnt lgkmcnt(0)
	s_barrier
	s_waitcnt vmcnt(0)
	v_mov_b32_e32 v52, v94
	v_mov_b32_e32 v53, v95
	v_mov_b32_e32 v54, v96
	v_mov_b32_e32 v55, v97
	v_mov_b32_e32 v44, v98
	v_mov_b32_e32 v45, v99
	v_mov_b32_e32 v46, v100
	v_mov_b32_e32 v47, v101
	v_mov_b32_e32 v56, v102
	v_mov_b32_e32 v57, v103
	v_mov_b32_e32 v58, v104
	v_mov_b32_e32 v59, v105
	v_mov_b32_e32 v48, v106
	v_mov_b32_e32 v49, v107
	v_mov_b32_e32 v50, v108
	v_mov_b32_e32 v51, v109
	v_mov_b32_e32 v36, v110
	v_mov_b32_e32 v37, v111
	v_mov_b32_e32 v38, v112
	v_mov_b32_e32 v39, v113
	v_mov_b32_e32 v28, v114
	v_mov_b32_e32 v29, v115
	v_mov_b32_e32 v30, v116
	v_mov_b32_e32 v31, v117
	v_mov_b32_e32 v40, v118
	v_mov_b32_e32 v41, v119
	v_mov_b32_e32 v42, v120
	v_mov_b32_e32 v43, v121
	v_mov_b32_e32 v32, v122
	v_mov_b32_e32 v33, v123
	v_mov_b32_e32 v34, v124
	v_mov_b32_e32 v35, v125
	v_mov_b32_e32 v20, v126
	v_mov_b32_e32 v21, v127
	v_mov_b32_e32 v22, v128
	v_mov_b32_e32 v23, v129
	v_mov_b32_e32 v12, v130
	v_mov_b32_e32 v13, v131
	v_mov_b32_e32 v14, v132
	v_mov_b32_e32 v15, v133
	v_mov_b32_e32 v24, v134
	v_mov_b32_e32 v25, v135
	v_mov_b32_e32 v26, v136
	v_mov_b32_e32 v27, v137
	v_mov_b32_e32 v16, v138
	v_mov_b32_e32 v17, v139
	v_mov_b32_e32 v18, v140
	v_mov_b32_e32 v19, v141
	v_mov_b32_e32 v8, v142
	v_mov_b32_e32 v9, v143
	v_mov_b32_e32 v10, v144
	v_mov_b32_e32 v11, v145
	v_mov_b32_e32 v0, v146
	v_mov_b32_e32 v1, v147
	v_mov_b32_e32 v2, v148
	v_mov_b32_e32 v3, v149
	v_mov_b32_e32 v4, v150
	v_mov_b32_e32 v5, v151
	v_mov_b32_e32 v6, v152
	v_mov_b32_e32 v7, v153
	v_mov_b32_e32 v64, v154
	v_mov_b32_e32 v65, v155
	v_mov_b32_e32 v66, v156
	v_mov_b32_e32 v67, v157
	s_and_saveexec_b64 s[4:5], s[0:1]
	s_cbranch_execz .LBB0_585
	v_cmp_ne_u32_e32 vcc, 0, v60
	s_and_saveexec_b64 s[6:7], vcc
	s_cbranch_execz .LBB0_582
	v_lshlrev_b32_e32 v60, 2, v68
	s_add_i32 s10, 0, 0x21820
	v_add3_u32 v60, s10, v60, -4
	ds_read_b32 v60, v60
	v_max_f32_e32 v68, v70, v70
	s_waitcnt lgkmcnt(0)
	v_max_f32_e32 v60, v60, v60
	v_max_f32_e32 v70, v68, v60

; #define PG8_STAGE(bufoff, gbase, voff) do { _Pragma("unroll") for (int _i = 0; _i < 2; ++_i) \
;         __builtin_amdgcn_global_load_lds((const unsigned*)((const char*)(gbase) + (voff)[_i]), (LAS unsigned*)(lds + (bufoff) + ldsw + _i * 8192), 16, 0, 0); } while (0)
; #define PG8_WAIT_V(n) asm volatile("s_waitcnt vmcnt(" #n ")" ::: "memory")
; #define PG8_BAR __builtin_amdgcn_s_barrier()
; template <class Epi, class Sched, bool ZERO>
; __device__ __forceinline__ void gemm_phase_acc(LAS unsigned char* lds, const Gemm g, const Sched& S, const Epi& E, f32x4 (&acc)[2][2][4][2]) {
;     ...
;     if constexpr (ZERO) {
; #pragma unroll
;     for (int a = 0; a < 2; ++a)
; #pragma unroll
;         for (int b = 0; b < 2; ++b)
; #pragma unroll
;             for (int m = 0; m < 4; ++m)
; #pragma unroll
;                 for (int n = 0; n < 2; ++n) acc[a][b][m][n] = (f32x4){0.f, 0.f, 0.f, 0.f};
;     }
;     ...
;     const char* cA = (const char*)g.A + (size_t)cur.pm * tstep; const char* cB = (const char*)g.Bt + (size_t)cur.pn * tstep;
;     PG8_STAGE(PG8_SB(0, 0), cB, voffB); PG8_STAGE(PG8_SA(0, 0), cA, voffA); PG8_STAGE(PG8_SB(0, 1), cB + hstep, voffB); PG8_STAGE(PG8_SA(0, 1), cA + hstep, voffA);
;     if (wr == 1) PG8_BAR;
;     PG8_WAIT_V(4); PG8_BAR;
;     PG8_STAGE(PG8_SB(1, 0), cB + kstep, voffB); PG8_STAGE(PG8_SA(1, 0), cA + kstep, voffA); PG8_STAGE(PG8_SB(1, 1), cB + hstep + kstep, voffB);
;     PG8_WAIT_V(6); PG8_BAR;
.LBB0_630:
	v_and_b32_e32 v15, 15, v13
	v_bfe_u32 v16, v13, 4, 2
	s_and_b32 s17, s3, 3
	v_lshl_or_b32 v85, s4, 6, v15
	v_lshlrev_b32_e32 v84, 4, v16
	s_lshl_b32 s3, s4, 13
	v_lshlrev_b32_e32 v13, 2, v13
	s_mov_b64 s[4:5], 0x80
	v_lshl_or_b32 v15, v15, 6, v84
	v_and_b32_e32 v13, 32, v13
	s_add_i32 m0, s11, 0x18000
	v_lshl_add_u64 v[6:7], v[6:7], 0, s[4:5]
	v_bitop3_b32 v16, v15, s3, v13 bitop3:0xde
	s_lshl_b32 s3, s17, 12
	s_waitcnt vmcnt(4)
	s_barrier
	global_load_lds_dwordx4 v[6:7], off
	v_lshl_add_u64 v[4:5], v[4:5], 0, s[4:5]
	s_add_i32 m0, s11, 0x1a000
	s_add_i32 s24, s11, 0x8000
	s_add_i32 s25, s11, 0xa000
	global_load_lds_dwordx4 v[4:5], off
	v_lshl_add_u64 v[2:3], v[2:3], 0, s[4:5]
	s_mov_b32 m0, s24
	s_add_u32 s26, s0, 0x40080
	global_load_lds_dwordx4 v[2:3], off
	v_lshl_add_u64 v[0:1], v[0:1], 0, s[4:5]
	s_mov_b32 m0, s25
	s_addc_u32 s27, s1, 0
	global_load_lds_dwordx4 v[0:1], off
	s_add_i32 m0, s11, 0x1c000
	v_lshl_add_u64 v[0:1], s[26:27], 0, v[50:51]
	global_load_lds_dwordx4 v[0:1], off
	v_lshl_add_u64 v[0:1], s[26:27], 0, v[62:63]
	s_add_i32 m0, s11, 0x1e000
	v_readlane_b32 s26, v254, 26
	global_load_lds_dwordx4 v[0:1], off
	v_lshlrev_b32_e32 v0, 14, v8
	v_and_b32_e32 v0, 0xffff8000, v0
	v_lshl_add_u32 v0, v9, 11, v0
	v_and_b32_e32 v1, 1, v8
	v_lshl_or_b32 v0, v1, 6, v0
	v_readlane_b32 s27, v254, 27
	s_add_u32 s26, s70, s26
	v_lshl_add_u32 v0, v10, 1, v0
	v_mov_b32_e32 v1, v51
	s_addc_u32 s27, s71, s27
	s_mov_b64 s[8:9], 0x40080
	v_lshl_add_u64 v[0:1], s[26:27], 0, v[0:1]
	v_lshl_add_u64 v[72:73], v[0:1], 0, s[8:9]
	v_lshlrev_b32_e32 v0, 14, v11
	v_and_b32_e32 v0, 0xffff8000, v0
	s_lshl_b32 s2, s2, 16
	v_lshl_add_u32 v0, v12, 11, v0
	v_and_b32_e32 v1, 1, v11
	s_and_b32 s2, s2, 0x180000
	v_lshl_or_b32 v0, v1, 6, v0
	s_add_u32 s2, s70, s2
	v_bitop3_b32 v13, v15, s3, v13 bitop3:0xde
	v_lshl_add_u32 v0, v14, 1, v0
	v_mov_b32_e32 v1, v51
	s_addc_u32 s3, s71, 0
	s_waitcnt vmcnt(6)
	v_lshl_add_u64 v[0:1], s[26:27], 0, v[0:1]
	s_add_u32 s26, s2, 0x2e00100
	s_addc_u32 s27, s3, 0
	s_add_i32 s31, s35, s6
	s_add_i32 s39, s22, s6
	s_add_i32 s41, s23, s6
	s_add_i32 s43, s33, s6
	v_lshl_add_u64 v[74:75], v[0:1], 0, s[8:9]
	s_mov_b32 s28, -2
	s_mov_b64 s[2:3], 0
	v_add_u32_e32 v86, s35, v13
	v_add_u32_e32 v87, 0, v16
	s_add_i32 s29, s11, 0xc000
	s_add_i32 s30, s11, 0xe000
	v_add_u32_e32 v88, s22, v13
	s_add_i32 s38, s31, 0x2000
	s_add_i32 s40, s39, 0x2000
	v_add_u32_e32 v89, s23, v13
	v_add_u32_e32 v90, s33, v13
	s_add_i32 s42, s41, 0x2000
	s_add_i32 s44, s43, 0x2000
	v_mov_b32_e32 v0, v51
	v_mov_b32_e32 v1, v51
	v_mov_b32_e32 v2, v51
	v_mov_b32_e32 v3, v51
	v_mov_b32_e32 v4, v51
	v_mov_b32_e32 v5, v51
	v_mov_b32_e32 v6, v51
	v_mov_b32_e32 v7, v51
	v_mov_b32_e32 v16, v51
	v_mov_b32_e32 v17, v51
	v_mov_b32_e32 v18, v51
	v_mov_b32_e32 v19, v51
	v_mov_b32_e32 v20, v51
	v_mov_b32_e32 v21, v51
	v_mov_b32_e32 v22, v51
	v_mov_b32_e32 v23, v51
	v_mov_b32_e32 v32, v51
	v_mov_b32_e32 v33, v51
	v_mov_b32_e32 v34, v51
	v_mov_b32_e32 v35, v51
	v_mov_b32_e32 v36, v51
	v_mov_b32_e32 v37, v51
	v_mov_b32_e32 v38, v51
	v_mov_b32_e32 v39, v51
	v_mov_b32_e32 v52, v51
	v_mov_b32_e32 v53, v51
	v_mov_b32_e32 v54, v51
	v_mov_b32_e32 v55, v51
	v_mov_b32_e32 v56, v51
	v_mov_b32_e32 v57, v51
	v_mov_b32_e32 v58, v51
	v_mov_b32_e32 v59, v51
	v_mov_b32_e32 v8, v51
	v_mov_b32_e32 v9, v51
	v_mov_b32_e32 v10, v51
	v_mov_b32_e32 v11, v51
	v_mov_b32_e32 v12, v51
	v_mov_b32_e32 v13, v51
	v_mov_b32_e32 v14, v51
	v_mov_b32_e32 v15, v51
	v_mov_b32_e32 v24, v51
	v_mov_b32_e32 v25, v51
	v_mov_b32_e32 v26, v51
	v_mov_b32_e32 v27, v51
	v_mov_b32_e32 v28, v51
	v_mov_b32_e32 v29, v51
	v_mov_b32_e32 v30, v51
	v_mov_b32_e32 v31, v51
	v_mov_b32_e32 v40, v51
	v_mov_b32_e32 v41, v51
	v_mov_b32_e32 v42, v51
	v_mov_b32_e32 v43, v51
	v_mov_b32_e32 v44, v51
	v_mov_b32_e32 v45, v51
	v_mov_b32_e32 v46, v51
	v_mov_b32_e32 v47, v51
	v_mov_b32_e32 v64, v51
	v_mov_b32_e32 v65, v51
	v_mov_b32_e32 v66, v51
	v_mov_b32_e32 v67, v51
	v_mov_b32_e32 v68, v51
	v_mov_b32_e32 v69, v51
	v_mov_b32_e32 v70, v51
	v_mov_b32_e32 v71, v51
	v_mov_b32_e32 v76, v51
	v_mov_b32_e32 v77, v51
	v_mov_b32_e32 v78, v51
	v_mov_b32_e32 v79, v51
	v_mov_b32_e32 v80, v51
	v_mov_b32_e32 v81, v51
	v_mov_b32_e32 v82, v51
	v_mov_b32_e32 v83, v51
	v_mov_b32_e32 v104, v51
	v_mov_b32_e32 v105, v51
	v_mov_b32_e32 v106, v51
	v_mov_b32_e32 v107, v51
	v_mov_b32_e32 v108, v51
	v_mov_b32_e32 v109, v51
	v_mov_b32_e32 v110, v51
	v_mov_b32_e32 v111, v51
	v_mov_b32_e32 v128, v51
	v_mov_b32_e32 v129, v51
	v_mov_b32_e32 v130, v51
	v_mov_b32_e32 v131, v51
	v_mov_b32_e32 v132, v51
	v_mov_b32_e32 v133, v51
	v_mov_b32_e32 v134, v51
	v_mov_b32_e32 v135, v51
	v_mov_b32_e32 v144, v51
	v_mov_b32_e32 v145, v51
	v_mov_b32_e32 v146, v51
	v_mov_b32_e32 v147, v51
	v_mov_b32_e32 v148, v51
	v_mov_b32_e32 v149, v51
	v_mov_b32_e32 v150, v51
	v_mov_b32_e32 v151, v51
	v_mov_b32_e32 v92, v51
	v_mov_b32_e32 v93, v51
	v_mov_b32_e32 v94, v51
	v_mov_b32_e32 v95, v51
	v_mov_b32_e32 v96, v51
	v_mov_b32_e32 v97, v51
	v_mov_b32_e32 v98, v51
	v_mov_b32_e32 v99, v51
	v_mov_b32_e32 v116, v51
	v_mov_b32_e32 v117, v51
	v_mov_b32_e32 v118, v51
	v_mov_b32_e32 v119, v51
	v_mov_b32_e32 v120, v51
	v_mov_b32_e32 v121, v51
	v_mov_b32_e32 v122, v51
	v_mov_b32_e32 v123, v51
	v_mov_b32_e32 v136, v51
	v_mov_b32_e32 v137, v51
	v_mov_b32_e32 v138, v51
	v_mov_b32_e32 v139, v51
	v_mov_b32_e32 v140, v51
	v_mov_b32_e32 v141, v51
	v_mov_b32_e32 v142, v51
	v_mov_b32_e32 v143, v51
	v_mov_b32_e32 v152, v51
	v_mov_b32_e32 v153, v51
	v_mov_b32_e32 v154, v51
	v_mov_b32_e32 v155, v51
	v_mov_b32_e32 v156, v51
	v_mov_b32_e32 v157, v51
	v_mov_b32_e32 v158, v51
	v_mov_b32_e32 v159, v51
	s_barrier
	s_nop 0
	s_nop 0
	s_nop 0
